# P0 non-critical weight transposes (w_glu,w_mkv,w_out0) deferred to P1 head on half the CUs (power-refunded stagger) + scan nops removed
# speedup vs baseline: 1.0067x; 1.0028x over previous
.LBB0_5:
	s_or_b64 exec, exec, s[4:5]
	s_load_dwordx16 s[44:59], s[0:1], 0x40
	s_lshl_b32 s96, s94, 3
	s_lshl_b32 s1, s2, 3
	s_add_u32 s4, s92, 0x3500000
	s_addc_u32 s5, s93, 0
	v_writelane_b32 v233, s4, 18
	v_mov_b32_e32 v1, v210
	s_add_u32 s62, s92, 0x400000
	v_writelane_b32 v233, s5, 19
	v_writelane_b32 v233, s1, 20
	s_waitcnt lgkmcnt(0)
	v_writelane_b32 v233, s44, 21
	s_addc_u32 s63, s93, 0
	v_readfirstlane_b32 s0, v1
	v_writelane_b32 v233, s45, 22
	v_writelane_b32 v233, s46, 23
	v_writelane_b32 v233, s47, 24
	v_writelane_b32 v233, s48, 25
	v_writelane_b32 v233, s49, 26
	v_writelane_b32 v233, s50, 27
	v_writelane_b32 v233, s51, 28
	v_writelane_b32 v233, s52, 29
	v_writelane_b32 v233, s53, 30
	v_writelane_b32 v233, s54, 31
	v_writelane_b32 v233, s55, 32
	s_ashr_i32 s8, s0, 6
	v_writelane_b32 v233, s56, 33
	s_add_i32 s26, s8, s1
	v_writelane_b32 v233, s57, 34
	s_mov_b32 s100, 0
	s_movk_i32 s101, 0xfff
	s_cmp_gt_i32 s26, s101
	v_and_b32_e32 v76, 63, v1
	v_writelane_b32 v233, s58, 35
	v_writelane_b32 v233, s59, 36
	s_cbranch_scc1 .LBB0_30
.Lp0_setup:
	s_add_u32 s0, s74, 0x800000
	s_addc_u32 s1, s75, 0
	v_readlane_b32 s40, v233, 2
	s_cmp_lg_u64 s[72:73], 0
	v_readlane_b32 s44, v233, 6
	v_readlane_b32 s45, v233, 7
	s_cselect_b64 s[4:5], -1, 0
	s_cmp_lg_u64 s[44:45], 0
	s_cselect_b64 s[6:7], -1, 0
	s_lshl_b32 s8, s8, 14
	v_lshrrev_b32_e32 v28, 5, v76
	v_and_b32_e32 v2, 31, v1
	v_and_b32_e32 v3, 7, v1
	v_lshrrev_b32_e32 v30, 3, v76
	s_add_i32 s10, s8, 0
	v_mov_b32_e32 v11, 0
	v_lshlrev_b32_e32 v4, 2, v2
	v_mul_u32_u24_e32 v5, 0x84, v28
	v_mul_u32_u24_e32 v6, 0x420, v3
	v_lshlrev_b32_e32 v10, 4, v3
	v_lshlrev_b32_e32 v7, 2, v30
	v_add3_u32 v29, s10, v4, v5
	v_lshl_add_u64 v[4:5], s[92:93], 0, v[10:11]
	s_mov_b64 s[8:9], 0x3d00000
	v_add3_u32 v31, s10, v6, v7
	v_lshlrev_b32_e32 v6, 5, v3
	v_mov_b32_e32 v7, v11
	v_lshl_add_u64 v[12:13], v[4:5], 0, s[8:9]
	v_lshl_add_u64 v[14:15], s[72:73], 0, v[6:7]
	s_mov_b64 s[8:9], 0x2000
	v_lshl_add_u64 v[16:17], v[14:15], 0, s[8:9]
	s_mov_b64 s[8:9], 0x3900000
	v_lshl_add_u64 v[18:19], v[4:5], 0, s[8:9]
	s_mov_b64 s[8:9], 0x3000000
	v_lshl_add_u64 v[20:21], v[4:5], 0, s[8:9]
	v_readlane_b32 s8, v233, 18
	v_readlane_b32 s46, v233, 8
	v_readlane_b32 s47, v233, 9
	v_readlane_b32 s48, v233, 10
	v_readlane_b32 s49, v233, 11
	v_readlane_b32 s50, v233, 12
	v_readlane_b32 s51, v233, 13
	v_readlane_b32 s52, v233, 14
	v_readlane_b32 s53, v233, 15
	v_readlane_b32 s54, v233, 16
	v_readlane_b32 s55, v233, 17
	v_readlane_b32 s9, v233, 19
	v_readlane_b32 s41, v233, 3
	v_lshl_add_u64 v[22:23], s[44:45], 0, v[6:7]
	v_readlane_b32 s44, v233, 21
	v_lshl_add_u64 v[24:25], s[8:9], 0, v[10:11]
	s_lshl_b32 s8, s26, 1
	v_or_b32_e32 v32, 8, v30
	v_or_b32_e32 v33, 16, v30
	v_or_b32_e32 v34, 24, v30
	v_readlane_b32 s45, v233, 22
	v_readlane_b32 s46, v233, 23
	v_readlane_b32 s47, v233, 24
	v_readlane_b32 s48, v233, 25
	v_readlane_b32 s49, v233, 26
	v_readlane_b32 s50, v233, 27
	v_readlane_b32 s51, v233, 28
	v_readlane_b32 s54, v233, 31
	v_readlane_b32 s55, v233, 32
	v_readlane_b32 s58, v233, 35
	v_readlane_b32 s59, v233, 36
	v_lshl_add_u64 v[26:27], s[62:63], 0, v[10:11]
	s_lshl_b32 s10, s26, 5
	s_lshl_b32 s11, s96, 5
	s_add_i32 s12, s8, 0x1cf00
	s_lshl_b32 s13, s96, 1
	s_movk_i32 s14, 0x4000
	s_mov_b32 s15, 0x8000
	s_mov_b32 s17, 0xc000
	s_mov_b32 s19, 0x10000
	s_mov_b32 s20, 0x14000
	s_mov_b32 s21, 0x18000
	s_mov_b32 s22, 0x1c000
	s_mov_b32 s23, 0x20000
	s_mov_b32 s27, 0x24000
	s_mov_b32 s30, 0x28000
	s_mov_b32 s31, 0x2c000
	s_mov_b32 s33, 0x30000
	s_mov_b32 s34, 0x34000
	s_mov_b32 s35, 0x38000
	s_mov_b32 s36, 0x3c000
	s_mov_b32 s37, 0x48000
	v_lshlrev_b32_e32 v10, 2, v2
	v_add_u32_e32 v35, 0x400, v29
	v_add_u32_e32 v36, 0x800, v29
	v_add_u32_e32 v37, 0xc00, v29
	v_add_u32_e32 v38, 0x1000, v29
	v_add_u32_e32 v39, 0x1400, v29
	v_add_u32_e32 v40, 0x1800, v29
	v_add_u32_e32 v41, 0x1c00, v29
	s_mov_b32 s40, 0xe8000
	s_mov_b32 s41, s26
	s_mov_b32 s29, 0
	v_readlane_b32 s42, v233, 4
	v_readlane_b32 s43, v233, 5
	v_readlane_b32 s52, v233, 29
	v_readlane_b32 s53, v233, 30
	v_readlane_b32 s56, v233, 33
	v_readlane_b32 s57, v233, 34
	s_branch .LBB0_10

.LBB0_9:
	s_add_i32 s41, s41, s96
	s_add_i32 s10, s10, s11
	s_add_i32 s12, s12, s13
	s_cmp_gt_i32 s41, s101
	s_cbranch_scc1 .LBB0_30

.LBB0_30:
	s_cmp_eq_u32 s100, 1
	s_cbranch_scc1 .Lp1_ret
	s_add_u32 s6, s92, 0x4d00000
	s_addc_u32 s7, s93, 0
	s_cmpk_gt_i32 s26, 0x3fff
	v_lshlrev_b32_e32 v66, 4, v76
	v_cmp_ne_u32_e64 s[4:5], 0, v76
	v_lshlrev_b32_e32 v68, 3, v76
	s_cbranch_scc1 .LBB0_40
	s_ashr_i32 s27, s26, 31
	s_lshl_b64 s[0:1], s[26:27], 13
	v_readlane_b32 s40, v233, 2
	v_readlane_b32 s41, v233, 3
	s_add_u32 s0, s40, s0
	s_addc_u32 s1, s41, s1
	v_mov_b32_e32 v67, 0
	v_lshl_add_u64 v[2:3], s[0:1], 0, v[66:67]
	global_load_dwordx4 v[62:65], v66, s[0:1] nt
	global_load_dwordx4 v[58:61], v66, s[0:1] offset:1024 nt
	global_load_dwordx4 v[54:57], v66, s[0:1] offset:2048 nt
	global_load_dwordx4 v[46:49], v66, s[0:1] offset:3072 nt
	s_movk_i32 s0, 0x1000
	v_add_co_u32_e32 v2, vcc, s0, v2
	s_lshl_b64 s[0:1], s[26:27], 2
	s_nop 0
	v_addc_co_u32_e32 v3, vcc, 0, v3, vcc
	global_load_dwordx4 v[50:53], v[2:3], off nt
	global_load_dwordx4 v[42:45], v[2:3], off offset:1024 nt
	global_load_dwordx4 v[38:41], v[2:3], off offset:2048 nt
	global_load_dwordx4 v[34:37], v[2:3], off offset:3072 nt
	s_add_u32 s8, s92, s0
	v_mov_b32_e32 v69, v67
	s_addc_u32 s9, s93, s1
	s_ashr_i32 s97, s96, 31
	v_lshl_add_u64 v[70:71], s[40:41], 0, v[66:67]
	v_lshl_add_u64 v[72:73], s[6:7], 0, v[68:69]
	s_lshl_b64 s[10:11], s[96:97], 2
	v_mov_b32_e32 v69, 0x358637bd
	s_mov_b32 s17, 0xf800000
	v_mov_b32_e32 v77, 0x260
	s_mov_b64 s[12:13], s[26:27]
	v_readlane_b32 s42, v233, 4
	v_readlane_b32 s43, v233, 5
	v_readlane_b32 s44, v233, 6
	v_readlane_b32 s45, v233, 7
	v_readlane_b32 s46, v233, 8
	v_readlane_b32 s47, v233, 9
	v_readlane_b32 s48, v233, 10
	v_readlane_b32 s49, v233, 11
	v_readlane_b32 s50, v233, 12
	v_readlane_b32 s51, v233, 13
	v_readlane_b32 s52, v233, 14
	v_readlane_b32 s53, v233, 15
	v_readlane_b32 s54, v233, 16
	v_readlane_b32 s55, v233, 17
	s_branch .LBB0_33

.LBB0_128:
	s_or_b64 exec, exec, s[0:1]
	s_bitcmp1_b32 s2, 3
	s_cbranch_scc0 .Lp1_skipdefer
	v_writelane_b32 v234, s0, 0
	v_writelane_b32 v234, s1, 1
	v_writelane_b32 v234, s2, 2
	v_writelane_b32 v234, s3, 3
	v_writelane_b32 v234, s4, 4
	v_writelane_b32 v234, s5, 5
	v_writelane_b32 v234, s6, 6
	v_writelane_b32 v234, s7, 7
	v_writelane_b32 v234, s8, 8
	v_writelane_b32 v234, s9, 9
	v_writelane_b32 v234, s10, 10
	v_writelane_b32 v234, s11, 11
	v_writelane_b32 v234, s12, 12
	v_writelane_b32 v234, s13, 13
	v_writelane_b32 v234, s14, 14
	v_writelane_b32 v234, s15, 15
	v_writelane_b32 v234, s16, 16
	v_writelane_b32 v234, s17, 17
	v_writelane_b32 v234, s18, 18
	v_writelane_b32 v234, s19, 19
	v_writelane_b32 v234, s20, 20
	v_writelane_b32 v234, s21, 21
	v_writelane_b32 v234, s22, 22
	v_writelane_b32 v234, s23, 23
	v_writelane_b32 v234, s24, 24
	v_writelane_b32 v234, s25, 25
	v_writelane_b32 v234, s26, 26
	v_writelane_b32 v234, s27, 27
	v_writelane_b32 v234, s28, 28
	v_writelane_b32 v234, s29, 29
	v_writelane_b32 v234, s30, 30
	v_writelane_b32 v234, s31, 31
	v_writelane_b32 v234, s32, 32
	v_writelane_b32 v234, s33, 33
	v_writelane_b32 v234, s34, 34
	v_writelane_b32 v234, s35, 35
	v_writelane_b32 v234, s36, 36
	v_writelane_b32 v234, s37, 37
	v_writelane_b32 v234, s38, 38
	v_writelane_b32 v234, s39, 39
	v_writelane_b32 v234, s40, 40
	v_writelane_b32 v234, s41, 41
	v_writelane_b32 v234, s42, 42
	v_writelane_b32 v234, s43, 43
	v_writelane_b32 v234, s44, 44
	v_writelane_b32 v234, s45, 45
	v_writelane_b32 v234, s46, 46
	v_writelane_b32 v234, s47, 47
	v_writelane_b32 v234, s48, 48
	v_writelane_b32 v234, s49, 49
	v_writelane_b32 v234, s50, 50
	v_writelane_b32 v234, s51, 51
	v_writelane_b32 v234, s52, 52
	v_writelane_b32 v234, s53, 53
	v_writelane_b32 v234, s54, 54
	v_writelane_b32 v234, s55, 55
	v_writelane_b32 v234, s56, 56
	v_writelane_b32 v234, s57, 57
	v_writelane_b32 v234, s58, 58
	v_writelane_b32 v234, s59, 59
	v_writelane_b32 v234, s60, 60
	v_writelane_b32 v234, s61, 61
	v_writelane_b32 v234, s62, 62
	v_writelane_b32 v234, s63, 63
	v_writelane_b32 v235, s64, 0
	v_writelane_b32 v235, s65, 1
	v_writelane_b32 v235, s66, 2
	v_writelane_b32 v235, s67, 3
	v_writelane_b32 v235, s68, 4
	v_writelane_b32 v235, s69, 5
	v_writelane_b32 v235, s70, 6
	v_writelane_b32 v235, s71, 7
	v_writelane_b32 v235, s72, 8
	v_writelane_b32 v235, s73, 9
	v_writelane_b32 v235, s74, 10
	v_writelane_b32 v235, s75, 11
	v_writelane_b32 v235, s76, 12
	v_writelane_b32 v235, s77, 13
	v_writelane_b32 v235, s78, 14
	v_writelane_b32 v235, s79, 15
	v_writelane_b32 v235, s80, 16
	v_writelane_b32 v235, s81, 17
	v_writelane_b32 v235, s82, 18
	v_writelane_b32 v235, s83, 19
	v_writelane_b32 v235, s84, 20
	v_writelane_b32 v235, s85, 21
	v_writelane_b32 v235, s86, 22
	v_writelane_b32 v235, s87, 23
	v_writelane_b32 v235, s88, 24
	v_writelane_b32 v235, s89, 25
	v_writelane_b32 v235, s90, 26
	v_writelane_b32 v235, s91, 27
	v_writelane_b32 v235, s92, 28
	v_writelane_b32 v235, s93, 29
	v_writelane_b32 v235, s94, 30
	v_writelane_b32 v235, s95, 31
	v_writelane_b32 v235, s96, 32
	v_writelane_b32 v235, s97, 33
	v_writelane_b32 v235, vcc_lo, 34
	v_writelane_b32 v235, vcc_hi, 35
	v_readlane_b32 s72, v233, 47
	v_readlane_b32 s73, v233, 48
	v_readlane_b32 s74, v233, 49
	v_readlane_b32 s75, v233, 50
	v_readlane_b32 s76, v233, 51
	v_readlane_b32 s77, v233, 52
	s_add_u32 s62, s92, 0x400000
	s_addc_u32 s63, s93, 0
	v_mov_b32_e32 v1, v210
	s_nop 0
	v_readfirstlane_b32 s0, v1
	v_and_b32_e32 v76, 63, v1
	s_nop 3
	s_ashr_i32 s8, s0, 6
	s_lshr_b32 s1, s2, 4
	s_lshl_b32 s1, s1, 3
	s_and_b32 s3, s2, 7
	s_or_b32 s1, s1, s3
	s_lshl_b32 s1, s1, 3
	s_add_i32 s26, s8, s1
	s_addk_i32 s26, 0x1000
	s_movk_i32 s96, 0x400
	s_movk_i32 s101, 0x247f
	s_mov_b32 s100, 1
	s_branch .Lp0_setup
.Lp1_ret:
	s_waitcnt lgkmcnt(0)
	v_readlane_b32 s0, v234, 0
	v_readlane_b32 s1, v234, 1
	v_readlane_b32 s2, v234, 2
	v_readlane_b32 s3, v234, 3
	v_readlane_b32 s4, v234, 4
	v_readlane_b32 s5, v234, 5
	v_readlane_b32 s6, v234, 6
	v_readlane_b32 s7, v234, 7
	v_readlane_b32 s8, v234, 8
	v_readlane_b32 s9, v234, 9
	v_readlane_b32 s10, v234, 10
	v_readlane_b32 s11, v234, 11
	v_readlane_b32 s12, v234, 12
	v_readlane_b32 s13, v234, 13
	v_readlane_b32 s14, v234, 14
	v_readlane_b32 s15, v234, 15
	v_readlane_b32 s16, v234, 16
	v_readlane_b32 s17, v234, 17
	v_readlane_b32 s18, v234, 18
	v_readlane_b32 s19, v234, 19
	v_readlane_b32 s20, v234, 20
	v_readlane_b32 s21, v234, 21
	v_readlane_b32 s22, v234, 22
	v_readlane_b32 s23, v234, 23
	v_readlane_b32 s24, v234, 24
	v_readlane_b32 s25, v234, 25
	v_readlane_b32 s26, v234, 26
	v_readlane_b32 s27, v234, 27
	v_readlane_b32 s28, v234, 28
	v_readlane_b32 s29, v234, 29
	v_readlane_b32 s30, v234, 30
	v_readlane_b32 s31, v234, 31
	v_readlane_b32 s32, v234, 32
	v_readlane_b32 s33, v234, 33
	v_readlane_b32 s34, v234, 34
	v_readlane_b32 s35, v234, 35
	v_readlane_b32 s36, v234, 36
	v_readlane_b32 s37, v234, 37
	v_readlane_b32 s38, v234, 38
	v_readlane_b32 s39, v234, 39
	v_readlane_b32 s40, v234, 40
	v_readlane_b32 s41, v234, 41
	v_readlane_b32 s42, v234, 42
	v_readlane_b32 s43, v234, 43
	v_readlane_b32 s44, v234, 44
	v_readlane_b32 s45, v234, 45
	v_readlane_b32 s46, v234, 46
	v_readlane_b32 s47, v234, 47
	v_readlane_b32 s48, v234, 48
	v_readlane_b32 s49, v234, 49
	v_readlane_b32 s50, v234, 50
	v_readlane_b32 s51, v234, 51
	v_readlane_b32 s52, v234, 52
	v_readlane_b32 s53, v234, 53
	v_readlane_b32 s54, v234, 54
	v_readlane_b32 s55, v234, 55
	v_readlane_b32 s56, v234, 56
	v_readlane_b32 s57, v234, 57
	v_readlane_b32 s58, v234, 58
	v_readlane_b32 s59, v234, 59
	v_readlane_b32 s60, v234, 60
	v_readlane_b32 s61, v234, 61
	v_readlane_b32 s62, v234, 62
	v_readlane_b32 s63, v234, 63
	v_readlane_b32 s64, v235, 0
	v_readlane_b32 s65, v235, 1
	v_readlane_b32 s66, v235, 2
	v_readlane_b32 s67, v235, 3
	v_readlane_b32 s68, v235, 4
	v_readlane_b32 s69, v235, 5
	v_readlane_b32 s70, v235, 6
	v_readlane_b32 s71, v235, 7
	v_readlane_b32 s72, v235, 8
	v_readlane_b32 s73, v235, 9
	v_readlane_b32 s74, v235, 10
	v_readlane_b32 s75, v235, 11
	v_readlane_b32 s76, v235, 12
	v_readlane_b32 s77, v235, 13
	v_readlane_b32 s78, v235, 14
	v_readlane_b32 s79, v235, 15
	v_readlane_b32 s80, v235, 16
	v_readlane_b32 s81, v235, 17
	v_readlane_b32 s82, v235, 18
	v_readlane_b32 s83, v235, 19
	v_readlane_b32 s84, v235, 20
	v_readlane_b32 s85, v235, 21
	v_readlane_b32 s86, v235, 22
	v_readlane_b32 s87, v235, 23
	v_readlane_b32 s88, v235, 24
	v_readlane_b32 s89, v235, 25
	v_readlane_b32 s90, v235, 26
	v_readlane_b32 s91, v235, 27
	v_readlane_b32 s92, v235, 28
	v_readlane_b32 s93, v235, 29
	v_readlane_b32 s94, v235, 30
	v_readlane_b32 s95, v235, 31
	v_readlane_b32 s96, v235, 32
	v_readlane_b32 s97, v235, 33
	v_readlane_b32 vcc_lo, v235, 34
	v_readlane_b32 vcc_hi, v235, 35
	s_nop 4
.Lp1_skipdefer:
	s_cmpk_lt_i32 s2, 0x400
	v_mov_b32_e32 v8, v210
	v_writelane_b32 v232, s24, 47
	s_waitcnt lgkmcnt(0)
	s_barrier
	s_cselect_b64 s[0:1], -1, 0
	s_cmpk_gt_i32 s2, 0x3ff
	v_writelane_b32 v232, s25, 48
	v_readfirstlane_b32 s4, v8
	s_cbranch_scc1 .LBB0_130
	s_ashr_i32 s3, s2, 31
	s_lshr_b32 s3, s3, 29
	s_add_i32 s3, s2, s3
	s_and_b32 s5, s3, -8
	s_sub_i32 s5, s2, s5
	s_lshl_b32 s13, s5, 7
	s_ashr_i32 s3, s3, 3
	s_mul_i32 s12, s5, 0x81
	s_cmp_lt_i32 s5, 0
	s_cselect_b32 s5, s12, s13
	s_add_i32 s3, s5, s3
	s_ashr_i32 s5, s3, 31
	s_lshr_b32 s5, s5, 26
	s_add_i32 s5, s3, s5
	s_ashr_i32 s12, s5, 6
	s_andn2_b32 s5, s5, 63
	s_sub_i32 s3, s3, s5
	s_bfe_i32 s5, s3, 0x80000
	s_bfe_u32 s5, s5, 0x2000d
	s_add_i32 s5, s3, s5
	s_bfe_i32 s13, s5, 0x80000
	s_and_b32 s5, s5, 0xfc
	s_sub_i32 s3, s3, s5
	s_lshl_b32 s12, s12, 2
	s_sext_i32_i16 s13, s13
	s_sext_i32_i8 s3, s3
	s_add_i32 s14, s12, s3
	s_ashr_i32 s12, s13, 2

	.amdhsa_kernel _Z8yoco_fwd6Params
		.amdhsa_group_segment_fixed_size 0
		.amdhsa_private_segment_fixed_size 0
		.amdhsa_kernarg_size 456
		.amdhsa_user_sgpr_count 2
		.amdhsa_user_sgpr_dispatch_ptr 0
		.amdhsa_user_sgpr_queue_ptr 0
		.amdhsa_user_sgpr_kernarg_segment_ptr 1
		.amdhsa_user_sgpr_dispatch_id 0
		.amdhsa_user_sgpr_kernarg_preload_length 0
		.amdhsa_user_sgpr_kernarg_preload_offset 0
		.amdhsa_user_sgpr_private_segment_size 0
		.amdhsa_uses_dynamic_stack 0
		.amdhsa_enable_private_segment 0
		.amdhsa_system_sgpr_workgroup_id_x 1
		.amdhsa_system_sgpr_workgroup_id_y 0
		.amdhsa_system_sgpr_workgroup_id_z 0
		.amdhsa_system_sgpr_workgroup_info 0
		.amdhsa_system_vgpr_workitem_id 2
		.amdhsa_next_free_vgpr 240
		.amdhsa_next_free_sgpr 102
		.amdhsa_accum_offset 240
		.amdhsa_reserve_vcc 1
		.amdhsa_float_round_mode_32 0
		.amdhsa_float_round_mode_16_64 0
		.amdhsa_float_denorm_mode_32 3
		.amdhsa_float_denorm_mode_16_64 3
		.amdhsa_dx10_clamp 1
		.amdhsa_ieee_mode 1
		.amdhsa_fp16_overflow 0
		.amdhsa_tg_split 0
		.amdhsa_exception_fp_ieee_invalid_op 0
		.amdhsa_exception_fp_denorm_src 0
		.amdhsa_exception_fp_ieee_div_zero 0
		.amdhsa_exception_fp_ieee_overflow 0
		.amdhsa_exception_fp_ieee_underflow 0
		.amdhsa_exception_fp_ieee_inexact 0
		.amdhsa_exception_int_div_zero 0
	.end_amdhsa_kernel

amdhsa.kernels:
  - .agpr_count:     0
    .args:
      - .offset:         0
        .size:           200
        .value_kind:     by_value
      - .offset:         200
        .size:           4
        .value_kind:     hidden_block_count_x
      - .offset:         204
        .size:           4
        .value_kind:     hidden_block_count_y
      - .offset:         208
        .size:           4
        .value_kind:     hidden_block_count_z
      - .offset:         212
        .size:           2
        .value_kind:     hidden_group_size_x
      - .offset:         214
        .size:           2
        .value_kind:     hidden_group_size_y
      - .offset:         216
        .size:           2
        .value_kind:     hidden_group_size_z
      - .offset:         218
        .size:           2
        .value_kind:     hidden_remainder_x
      - .offset:         220
        .size:           2
        .value_kind:     hidden_remainder_y
      - .offset:         222
        .size:           2
        .value_kind:     hidden_remainder_z
      - .offset:         240
        .size:           8
        .value_kind:     hidden_global_offset_x
      - .offset:         248
        .size:           8
        .value_kind:     hidden_global_offset_y
      - .offset:         256
        .size:           8
        .value_kind:     hidden_global_offset_z
      - .offset:         264
        .size:           2
        .value_kind:     hidden_grid_dims
      - .offset:         288
        .size:           8
        .value_kind:     hidden_multigrid_sync_arg
      - .offset:         320
        .size:           4
        .value_kind:     hidden_dynamic_lds_size
    .group_segment_fixed_size: 0
    .kernarg_segment_align: 8
    .kernarg_segment_size: 456
    .language:       OpenCL C
    .language_version:
      - 2
      - 0
    .max_flat_workgroup_size: 512
    .name:           _Z8yoco_fwd6Params
    .private_segment_fixed_size: 0
    .sgpr_count:     108
    .sgpr_spill_count: 132
    .symbol:         _Z8yoco_fwd6Params.kd
    .uniform_work_group_size: 1
    .uses_dynamic_stack: false
    .vgpr_count:     240
    .vgpr_spill_count: 0
    .wavefront_size: 64
